# GLU prologue GEMM: all 16 weight-fragment loads hoisted ahead of the unrolled k-loop (no per-half-step L2 round trip)
# speedup vs baseline: 1.1072x; 1.0057x over previous
; DI int opaque_tid() { int t = threadIdx.x; asm volatile("" : "+v"(t)); return t; }
; template <int NT2>
; DI void glu_prologue(const Params& p, char* lds, int l, int tile0, int tile1) {
;     const int tid = opaque_tid(), lane = tid & 63, wid = tid >> 6, l15 = lane & 15, quad = lane >> 4;
;     __syncthreads();
; #pragma unroll
;     for (int tt = 0; tt < NT2; ++tt) {
;         const int tile = tt ? tile1 : tile0;
;         char* Ys = lds + tt * 33792;
;         const bf16_t* ysg = WS_PTR(const bf16_t, OFF_YS) + (size_t)tile * 64 * 256;
; #pragma unroll
;         for (int i = 0; i < 4; ++i) {
;             const int idx = tid + NTHR * i, row = idx >> 5, c16 = idx & 31;
;             *(u32x4*)(Ys + row * 528 + c16 * 16) = *(const u32x4*)(ysg + (size_t)row * 256 + c16 * 8);
;         }
;     }
;     __syncthreads();
;     f32x4 acc[NT2][4][2];
; #pragma unroll
;     for (int tt = 0; tt < NT2; ++tt)
; #pragma unroll
;         for (int mt = 0; mt < 4; ++mt) { acc[tt][mt][0] = (f32x4){0.f, 0.f, 0.f, 0.f}; acc[tt][mt][1] = (f32x4){0.f, 0.f, 0.f, 0.f}; }
;     const bf16_t* Wg = WS_PTR(const bf16_t, OFF_WGLU) + (size_t)l * 65536;
; #pragma unroll 2
;     for (int ks = 0; ks < 8; ++ks) {
;         bf16x8 bb[2];
; #pragma unroll
;         for (int nt = 0; nt < 2; ++nt) bb[nt] = *(const bf16x8*)(Wg + (wid * 32 + nt * 16 + l15) * 256 + 32 * ks + 8 * quad);
.LBB0_90:
	s_and_b64 vcc, exec, s[6:7]
	s_cbranch_vccz .LBB0_94
	s_ashr_i32 s35, s34, 31
	v_mov_b32_e32 v78, v212
	s_lshl_b64 s[8:9], s[34:35], 15
	v_readlane_b32 s40, v244, 46
	s_add_u32 s6, s40, s8
	v_lshlrev_b32_e32 v0, 4, v78
	v_ashrrev_i32_e32 v8, 5, v78
	v_readlane_b32 s47, v244, 47
	v_and_b32_e32 v0, 0x1f0, v0
	v_ashrrev_i32_e32 v9, 31, v8
	s_addc_u32 s7, s47, s9
	v_lshlrev_b64 v[10:11], 9, v[8:9]
	v_lshl_add_u64 v[12:13], s[6:7], 0, v[0:1]
	v_lshl_add_u64 v[2:3], v[12:13], 0, v[10:11]
	s_barrier
	global_load_dwordx4 v[2:5], v[2:3], off
	v_add_u32_e32 v6, 0, v0
	s_movk_i32 s46, 0x210
	v_mad_u64_u32 v[8:9], s[6:7], v8, s46, v[6:7]
	s_ashr_i32 s49, s48, 31
	v_and_b32_e32 v84, 15, v78
	v_ashrrev_i32_e32 v76, 6, v78
	v_bfe_u32 v79, v78, 4, 2
	v_mul_u32_u24_e32 v82, 0x210, v84
	s_waitcnt vmcnt(0)
	ds_write_b128 v8, v[2:5]
	v_add_u32_e32 v2, 0x200, v78
	v_ashrrev_i32_e32 v14, 5, v2
	v_ashrrev_i32_e32 v15, 31, v14
	v_lshlrev_b64 v[16:17], 9, v[14:15]
	v_lshl_add_u64 v[2:3], v[12:13], 0, v[16:17]
	global_load_dwordx4 v[2:5], v[2:3], off
	v_mad_u64_u32 v[14:15], s[6:7], v14, s46, v[6:7]
	s_waitcnt vmcnt(0)
	ds_write_b128 v14, v[2:5]
	v_add_u32_e32 v2, 0x400, v78
	v_ashrrev_i32_e32 v18, 5, v2
	v_ashrrev_i32_e32 v19, 31, v18
	v_lshlrev_b64 v[20:21], 9, v[18:19]
	v_lshl_add_u64 v[2:3], v[12:13], 0, v[20:21]
	global_load_dwordx4 v[2:5], v[2:3], off
	v_mad_u64_u32 v[18:19], s[6:7], v18, s46, v[6:7]
	s_waitcnt vmcnt(0)
	ds_write_b128 v18, v[2:5]
	v_add_u32_e32 v2, 0x600, v78
	v_ashrrev_i32_e32 v22, 5, v2
	v_ashrrev_i32_e32 v23, 31, v22
	v_lshlrev_b64 v[24:25], 9, v[22:23]
	v_lshl_add_u64 v[2:3], v[12:13], 0, v[24:25]
	global_load_dwordx4 v[2:5], v[2:3], off
	v_mad_u64_u32 v[6:7], s[6:7], v22, s46, v[6:7]
	s_lshl_b64 s[6:7], s[48:49], 15
	s_add_u32 s46, s40, s6
	s_addc_u32 s47, s47, s7
	v_lshl_add_u64 v[12:13], s[46:47], 0, v[0:1]
	v_lshlrev_b32_e32 v0, 8, v84
	s_mov_b64 s[46:47], 0
	s_waitcnt vmcnt(0)
	ds_write_b128 v6, v[2:5]
	v_lshl_add_u64 v[2:3], v[12:13], 0, v[10:11]
	global_load_dwordx4 v[2:5], v[2:3], off
	s_waitcnt vmcnt(0)
	ds_write_b128 v8, v[2:5] offset:33792
	v_lshl_add_u64 v[2:3], v[12:13], 0, v[16:17]
	global_load_dwordx4 v[2:5], v[2:3], off
	s_waitcnt vmcnt(0)
	ds_write_b128 v14, v[2:5] offset:33792
	v_lshl_add_u64 v[2:3], v[12:13], 0, v[20:21]
	global_load_dwordx4 v[2:5], v[2:3], off
	s_waitcnt vmcnt(0)
	ds_write_b128 v18, v[2:5] offset:33792
	v_lshl_add_u64 v[2:3], v[12:13], 0, v[24:25]
	global_load_dwordx4 v[2:5], v[2:3], off
	s_waitcnt vmcnt(0)
	ds_write_b128 v6, v[2:5] offset:33792
	v_lshl_or_b32 v2, v76, 13, v0
	v_ashrrev_i32_e32 v3, 31, v2
	v_lshlrev_b32_e32 v4, 4, v79
	v_lshlrev_b64 v[2:3], 1, v[2:3]
	v_or_b32_e32 v2, v2, v4
	v_lshl_add_u64 v[66:67], s[30:31], 0, v[2:3]
	v_add_co_u32_e32 v80, vcc, s87, v66
	s_nop 1
	v_addc_co_u32_e32 v81, vcc, 0, v67, vcc
	v_add_co_u32_e32 v102, vcc, s86, v66
	s_nop 1
	v_addc_co_u32_e32 v103, vcc, 0, v67, vcc
	global_load_dwordx4 v[104:107], v[80:81], off
	global_load_dwordx4 v[108:111], v[102:103], off
	global_load_dwordx4 v[112:115], v[80:81], off offset:64
	global_load_dwordx4 v[116:119], v[102:103], off offset:64
	global_load_dwordx4 v[120:123], v[80:81], off offset:128
	global_load_dwordx4 v[124:127], v[102:103], off offset:128
	global_load_dwordx4 v[128:131], v[80:81], off offset:192
	global_load_dwordx4 v[132:135], v[102:103], off offset:192
	global_load_dwordx4 v[140:143], v[80:81], off offset:256
	global_load_dwordx4 v[144:147], v[102:103], off offset:256
	global_load_dwordx4 v[148:151], v[80:81], off offset:320
	global_load_dwordx4 v[152:155], v[102:103], off offset:320
	global_load_dwordx4 v[156:159], v[80:81], off offset:384
	global_load_dwordx4 v[160:163], v[102:103], off offset:384
	global_load_dwordx4 v[164:167], v[80:81], off offset:448
	global_load_dwordx4 v[168:171], v[102:103], off offset:448
	v_mov_b32_e32 v2, 0
	v_add3_u32 v77, v82, v4, 0
	v_mov_b32_e32 v3, v2
	v_mov_b32_e32 v4, v2
	v_mov_b32_e32 v5, v2
	v_mov_b32_e32 v14, v2
	v_mov_b32_e32 v15, v2
	v_mov_b32_e32 v16, v2
	v_mov_b32_e32 v17, v2
	v_mov_b32_e32 v18, v2
	v_mov_b32_e32 v19, v2
	v_mov_b32_e32 v20, v2
	v_mov_b32_e32 v21, v2
	v_mov_b32_e32 v22, v2
	v_mov_b32_e32 v23, v2
	v_mov_b32_e32 v24, v2
	v_mov_b32_e32 v25, v2
	v_mov_b32_e32 v26, v2
	v_mov_b32_e32 v27, v2
	v_mov_b32_e32 v28, v2
	v_mov_b32_e32 v29, v2
	v_mov_b32_e32 v34, v2
	v_mov_b32_e32 v35, v2
	v_mov_b32_e32 v36, v2
	v_mov_b32_e32 v37, v2
	v_mov_b32_e32 v30, v2
	v_mov_b32_e32 v31, v2
	v_mov_b32_e32 v32, v2
	v_mov_b32_e32 v33, v2
	v_mov_b32_e32 v38, v2
	v_mov_b32_e32 v39, v2
	v_mov_b32_e32 v40, v2
	v_mov_b32_e32 v41, v2
	v_mov_b32_e32 v42, v2
	v_mov_b32_e32 v43, v2
	v_mov_b32_e32 v44, v2
	v_mov_b32_e32 v45, v2
	v_mov_b32_e32 v46, v2
	v_mov_b32_e32 v47, v2
	v_mov_b32_e32 v48, v2
	v_mov_b32_e32 v49, v2
	v_mov_b32_e32 v50, v2
	v_mov_b32_e32 v51, v2
	v_mov_b32_e32 v52, v2
	v_mov_b32_e32 v53, v2
	v_mov_b32_e32 v68, v2
	v_mov_b32_e32 v69, v2
	v_mov_b32_e32 v70, v2
	v_mov_b32_e32 v71, v2
	v_mov_b32_e32 v58, v2
	v_mov_b32_e32 v59, v2
	v_mov_b32_e32 v60, v2
	v_mov_b32_e32 v61, v2
	v_mov_b32_e32 v54, v2
	v_mov_b32_e32 v55, v2
	v_mov_b32_e32 v56, v2
	v_mov_b32_e32 v57, v2
	v_mov_b32_e32 v10, v2
	v_mov_b32_e32 v11, v2
	v_mov_b32_e32 v12, v2
	v_mov_b32_e32 v13, v2
	v_mov_b32_e32 v6, v2
	v_mov_b32_e32 v7, v2
	v_mov_b32_e32 v8, v2
	v_mov_b32_e32 v9, v2
	s_waitcnt lgkmcnt(0)
	s_barrier
; DI f32x4 mfma16(bf16x8 a, bf16x8 b, f32x4 c) { return __builtin_amdgcn_mfma_f32_16x16x32_bf16(a, b, c, 0, 0, 0); }
; template <int NT2>
; DI void glu_prologue(const Params& p, char* lds, int l, int tile0, int tile1) {
;     ...
; #pragma unroll 2
;     for (int ks = 0; ks < 8; ++ks) {
;         bf16x8 bb[2];
; #pragma unroll
;         for (int nt = 0; nt < 2; ++nt) bb[nt] = *(const bf16x8*)(Wg + (wid * 32 + nt * 16 + l15) * 256 + 32 * ks + 8 * quad);
; #pragma unroll
;         for (int tt = 0; tt < NT2; ++tt) {
;             const char* Ys = lds + tt * 33792;
;             bf16x8 a[4];
; #pragma unroll
;             for (int mt = 0; mt < 4; ++mt) a[mt] = *(const bf16x8*)(Ys + (mt * 16 + l15) * 528 + (32 * ks + 8 * quad) * 2);
; #pragma unroll
;             for (int mt = 0; mt < 4; ++mt)
; #pragma unroll
;                 for (int nt = 0; nt < 2; ++nt) acc[tt][mt][nt] = mfma16(bb[nt], a[mt], acc[tt][mt][nt]);
;         }
	s_waitcnt vmcnt(14)
	ds_read_b128 v[86:89], v77
	ds_read_b128 v[90:93], v77 offset:8448
	ds_read_b128 v[94:97], v77 offset:16896
	ds_read_b128 v[98:101], v77 offset:25344
	s_waitcnt lgkmcnt(3)
	v_mfma_f32_16x16x32_bf16 v[54:57], v[104:107], v[86:89], v[54:57]
	v_mfma_f32_16x16x32_bf16 v[58:61], v[108:111], v[86:89], v[58:61]
	s_waitcnt lgkmcnt(2)
	v_mfma_f32_16x16x32_bf16 v[68:71], v[104:107], v[90:93], v[68:71]
	v_mfma_f32_16x16x32_bf16 v[50:53], v[108:111], v[90:93], v[50:53]
	s_waitcnt lgkmcnt(1)
	v_mfma_f32_16x16x32_bf16 v[46:49], v[104:107], v[94:97], v[46:49]
	v_mfma_f32_16x16x32_bf16 v[42:45], v[108:111], v[94:97], v[42:45]
	s_waitcnt lgkmcnt(0)
	v_mfma_f32_16x16x32_bf16 v[38:41], v[104:107], v[98:101], v[38:41]
	v_mfma_f32_16x16x32_bf16 v[30:33], v[108:111], v[98:101], v[30:33]
	ds_read_b128 v[86:89], v77 offset:33792
	ds_read_b128 v[90:93], v77 offset:42240
	ds_read_b128 v[94:97], v77 offset:50688
	ds_read_b128 v[98:101], v77 offset:59136
	s_waitcnt lgkmcnt(3)
	v_mfma_f32_16x16x32_bf16 v[34:37], v[104:107], v[86:89], v[34:37]
	v_mfma_f32_16x16x32_bf16 v[26:29], v[108:111], v[86:89], v[26:29]
	s_waitcnt lgkmcnt(2)
	v_mfma_f32_16x16x32_bf16 v[22:25], v[104:107], v[90:93], v[22:25]
	v_mfma_f32_16x16x32_bf16 v[18:21], v[108:111], v[90:93], v[18:21]
	s_waitcnt lgkmcnt(1)
	v_mfma_f32_16x16x32_bf16 v[14:17], v[104:107], v[94:97], v[14:17]
	v_mfma_f32_16x16x32_bf16 v[2:5], v[108:111], v[94:97], v[2:5]
	s_waitcnt lgkmcnt(0)
	v_mfma_f32_16x16x32_bf16 v[10:13], v[104:107], v[98:101], v[10:13]
	v_mfma_f32_16x16x32_bf16 v[6:9], v[108:111], v[98:101], v[6:9]
	s_waitcnt vmcnt(12)
	ds_read_b128 v[86:89], v77 offset:64
	ds_read_b128 v[90:93], v77 offset:8512
	ds_read_b128 v[94:97], v77 offset:16960
	ds_read_b128 v[98:101], v77 offset:25408
	s_waitcnt lgkmcnt(3)
	v_mfma_f32_16x16x32_bf16 v[54:57], v[112:115], v[86:89], v[54:57]
	v_mfma_f32_16x16x32_bf16 v[58:61], v[116:119], v[86:89], v[58:61]
	s_waitcnt lgkmcnt(2)
	v_mfma_f32_16x16x32_bf16 v[68:71], v[112:115], v[90:93], v[68:71]
	v_mfma_f32_16x16x32_bf16 v[50:53], v[116:119], v[90:93], v[50:53]
	s_waitcnt lgkmcnt(1)
	v_mfma_f32_16x16x32_bf16 v[46:49], v[112:115], v[94:97], v[46:49]
	v_mfma_f32_16x16x32_bf16 v[42:45], v[116:119], v[94:97], v[42:45]
	s_waitcnt lgkmcnt(0)
	v_mfma_f32_16x16x32_bf16 v[38:41], v[112:115], v[98:101], v[38:41]
	v_mfma_f32_16x16x32_bf16 v[30:33], v[116:119], v[98:101], v[30:33]
	ds_read_b128 v[86:89], v77 offset:33856
	ds_read_b128 v[90:93], v77 offset:42304
	ds_read_b128 v[94:97], v77 offset:50752
	ds_read_b128 v[98:101], v77 offset:59200
	s_waitcnt lgkmcnt(3)
	v_mfma_f32_16x16x32_bf16 v[34:37], v[112:115], v[86:89], v[34:37]
	v_mfma_f32_16x16x32_bf16 v[26:29], v[116:119], v[86:89], v[26:29]
	s_waitcnt lgkmcnt(2)
	v_mfma_f32_16x16x32_bf16 v[22:25], v[112:115], v[90:93], v[22:25]
	v_mfma_f32_16x16x32_bf16 v[18:21], v[116:119], v[90:93], v[18:21]
	s_waitcnt lgkmcnt(1)
	v_mfma_f32_16x16x32_bf16 v[14:17], v[112:115], v[94:97], v[14:17]
	v_mfma_f32_16x16x32_bf16 v[2:5], v[116:119], v[94:97], v[2:5]
	s_waitcnt lgkmcnt(0)
	v_mfma_f32_16x16x32_bf16 v[10:13], v[112:115], v[98:101], v[10:13]
	v_mfma_f32_16x16x32_bf16 v[6:9], v[116:119], v[98:101], v[6:9]
	s_waitcnt vmcnt(10)
	ds_read_b128 v[86:89], v77 offset:128
	ds_read_b128 v[90:93], v77 offset:8576
	ds_read_b128 v[94:97], v77 offset:17024
	ds_read_b128 v[98:101], v77 offset:25472
	s_waitcnt lgkmcnt(3)
	v_mfma_f32_16x16x32_bf16 v[54:57], v[120:123], v[86:89], v[54:57]
	v_mfma_f32_16x16x32_bf16 v[58:61], v[124:127], v[86:89], v[58:61]
	s_waitcnt lgkmcnt(2)
	v_mfma_f32_16x16x32_bf16 v[68:71], v[120:123], v[90:93], v[68:71]
	v_mfma_f32_16x16x32_bf16 v[50:53], v[124:127], v[90:93], v[50:53]
	s_waitcnt lgkmcnt(1)
	v_mfma_f32_16x16x32_bf16 v[46:49], v[120:123], v[94:97], v[46:49]
	v_mfma_f32_16x16x32_bf16 v[42:45], v[124:127], v[94:97], v[42:45]
	s_waitcnt lgkmcnt(0)
	v_mfma_f32_16x16x32_bf16 v[38:41], v[120:123], v[98:101], v[38:41]
	v_mfma_f32_16x16x32_bf16 v[30:33], v[124:127], v[98:101], v[30:33]
	ds_read_b128 v[86:89], v77 offset:33920
	ds_read_b128 v[90:93], v77 offset:42368
	ds_read_b128 v[94:97], v77 offset:50816
	ds_read_b128 v[98:101], v77 offset:59264
	s_waitcnt lgkmcnt(3)
	v_mfma_f32_16x16x32_bf16 v[34:37], v[120:123], v[86:89], v[34:37]
	v_mfma_f32_16x16x32_bf16 v[26:29], v[124:127], v[86:89], v[26:29]
	s_waitcnt lgkmcnt(2)
	v_mfma_f32_16x16x32_bf16 v[22:25], v[120:123], v[90:93], v[22:25]
	v_mfma_f32_16x16x32_bf16 v[18:21], v[124:127], v[90:93], v[18:21]
	s_waitcnt lgkmcnt(1)
	v_mfma_f32_16x16x32_bf16 v[14:17], v[120:123], v[94:97], v[14:17]
	v_mfma_f32_16x16x32_bf16 v[2:5], v[124:127], v[94:97], v[2:5]
	s_waitcnt lgkmcnt(0)
	v_mfma_f32_16x16x32_bf16 v[10:13], v[120:123], v[98:101], v[10:13]
	v_mfma_f32_16x16x32_bf16 v[6:9], v[124:127], v[98:101], v[6:9]
	s_waitcnt vmcnt(8)
	ds_read_b128 v[86:89], v77 offset:192
	ds_read_b128 v[90:93], v77 offset:8640
	ds_read_b128 v[94:97], v77 offset:17088
	ds_read_b128 v[98:101], v77 offset:25536
	s_waitcnt lgkmcnt(3)
	v_mfma_f32_16x16x32_bf16 v[54:57], v[128:131], v[86:89], v[54:57]
	v_mfma_f32_16x16x32_bf16 v[58:61], v[132:135], v[86:89], v[58:61]
	s_waitcnt lgkmcnt(2)
	v_mfma_f32_16x16x32_bf16 v[68:71], v[128:131], v[90:93], v[68:71]
	v_mfma_f32_16x16x32_bf16 v[50:53], v[132:135], v[90:93], v[50:53]
	s_waitcnt lgkmcnt(1)
	v_mfma_f32_16x16x32_bf16 v[46:49], v[128:131], v[94:97], v[46:49]
	v_mfma_f32_16x16x32_bf16 v[42:45], v[132:135], v[94:97], v[42:45]
	s_waitcnt lgkmcnt(0)
	v_mfma_f32_16x16x32_bf16 v[38:41], v[128:131], v[98:101], v[38:41]
	v_mfma_f32_16x16x32_bf16 v[30:33], v[132:135], v[98:101], v[30:33]
	ds_read_b128 v[86:89], v77 offset:33984
	ds_read_b128 v[90:93], v77 offset:42432
	ds_read_b128 v[94:97], v77 offset:50880
	ds_read_b128 v[98:101], v77 offset:59328
	s_waitcnt lgkmcnt(3)
; DI f32x4 mfma16(bf16x8 a, bf16x8 b, f32x4 c) { return __builtin_amdgcn_mfma_f32_16x16x32_bf16(a, b, c, 0, 0, 0); }
; template <int NT2>
; DI void glu_prologue(const Params& p, char* lds, int l, int tile0, int tile1) {
;     ...
; #pragma unroll 2
;     for (int ks = 0; ks < 8; ++ks) {
;         bf16x8 bb[2];
; #pragma unroll
;         for (int nt = 0; nt < 2; ++nt) bb[nt] = *(const bf16x8*)(Wg + (wid * 32 + nt * 16 + l15) * 256 + 32 * ks + 8 * quad);
; #pragma unroll
;         for (int tt = 0; tt < NT2; ++tt) {
;             const char* Ys = lds + tt * 33792;
;             bf16x8 a[4];
; #pragma unroll
;             for (int mt = 0; mt < 4; ++mt) a[mt] = *(const bf16x8*)(Ys + (mt * 16 + l15) * 528 + (32 * ks + 8 * quad) * 2);
; #pragma unroll
;             for (int mt = 0; mt < 4; ++mt)
; #pragma unroll
;                 for (int nt = 0; nt < 2; ++nt) acc[tt][mt][nt] = mfma16(bb[nt], a[mt], acc[tt][mt][nt]);
;         }
	v_mfma_f32_16x16x32_bf16 v[34:37], v[128:131], v[86:89], v[34:37]
	v_mfma_f32_16x16x32_bf16 v[26:29], v[132:135], v[86:89], v[26:29]
	s_waitcnt lgkmcnt(2)
	v_mfma_f32_16x16x32_bf16 v[22:25], v[128:131], v[90:93], v[22:25]
	v_mfma_f32_16x16x32_bf16 v[18:21], v[132:135], v[90:93], v[18:21]
	s_waitcnt lgkmcnt(1)
	v_mfma_f32_16x16x32_bf16 v[14:17], v[128:131], v[94:97], v[14:17]
	v_mfma_f32_16x16x32_bf16 v[2:5], v[132:135], v[94:97], v[2:5]
	s_waitcnt lgkmcnt(0)
	v_mfma_f32_16x16x32_bf16 v[10:13], v[128:131], v[98:101], v[10:13]
	v_mfma_f32_16x16x32_bf16 v[6:9], v[132:135], v[98:101], v[6:9]
	s_waitcnt vmcnt(6)
	ds_read_b128 v[86:89], v77 offset:256
	ds_read_b128 v[90:93], v77 offset:8704
	ds_read_b128 v[94:97], v77 offset:17152
	ds_read_b128 v[98:101], v77 offset:25600
	s_waitcnt lgkmcnt(3)
	v_mfma_f32_16x16x32_bf16 v[54:57], v[140:143], v[86:89], v[54:57]
	v_mfma_f32_16x16x32_bf16 v[58:61], v[144:147], v[86:89], v[58:61]
	s_waitcnt lgkmcnt(2)
	v_mfma_f32_16x16x32_bf16 v[68:71], v[140:143], v[90:93], v[68:71]
	v_mfma_f32_16x16x32_bf16 v[50:53], v[144:147], v[90:93], v[50:53]
	s_waitcnt lgkmcnt(1)
	v_mfma_f32_16x16x32_bf16 v[46:49], v[140:143], v[94:97], v[46:49]
	v_mfma_f32_16x16x32_bf16 v[42:45], v[144:147], v[94:97], v[42:45]
	s_waitcnt lgkmcnt(0)
	v_mfma_f32_16x16x32_bf16 v[38:41], v[140:143], v[98:101], v[38:41]
	v_mfma_f32_16x16x32_bf16 v[30:33], v[144:147], v[98:101], v[30:33]
	ds_read_b128 v[86:89], v77 offset:34048
	ds_read_b128 v[90:93], v77 offset:42496
	ds_read_b128 v[94:97], v77 offset:50944
	ds_read_b128 v[98:101], v77 offset:59392
	s_waitcnt lgkmcnt(3)
	v_mfma_f32_16x16x32_bf16 v[34:37], v[140:143], v[86:89], v[34:37]
	v_mfma_f32_16x16x32_bf16 v[26:29], v[144:147], v[86:89], v[26:29]
	s_waitcnt lgkmcnt(2)
	v_mfma_f32_16x16x32_bf16 v[22:25], v[140:143], v[90:93], v[22:25]
	v_mfma_f32_16x16x32_bf16 v[18:21], v[144:147], v[90:93], v[18:21]
	s_waitcnt lgkmcnt(1)
	v_mfma_f32_16x16x32_bf16 v[14:17], v[140:143], v[94:97], v[14:17]
	v_mfma_f32_16x16x32_bf16 v[2:5], v[144:147], v[94:97], v[2:5]
	s_waitcnt lgkmcnt(0)
	v_mfma_f32_16x16x32_bf16 v[10:13], v[140:143], v[98:101], v[10:13]
	v_mfma_f32_16x16x32_bf16 v[6:9], v[144:147], v[98:101], v[6:9]
	s_waitcnt vmcnt(4)
	ds_read_b128 v[86:89], v77 offset:320
	ds_read_b128 v[90:93], v77 offset:8768
	ds_read_b128 v[94:97], v77 offset:17216
	ds_read_b128 v[98:101], v77 offset:25664
	s_waitcnt lgkmcnt(3)
	v_mfma_f32_16x16x32_bf16 v[54:57], v[148:151], v[86:89], v[54:57]
	v_mfma_f32_16x16x32_bf16 v[58:61], v[152:155], v[86:89], v[58:61]
	s_waitcnt lgkmcnt(2)
	v_mfma_f32_16x16x32_bf16 v[68:71], v[148:151], v[90:93], v[68:71]
	v_mfma_f32_16x16x32_bf16 v[50:53], v[152:155], v[90:93], v[50:53]
	s_waitcnt lgkmcnt(1)
	v_mfma_f32_16x16x32_bf16 v[46:49], v[148:151], v[94:97], v[46:49]
	v_mfma_f32_16x16x32_bf16 v[42:45], v[152:155], v[94:97], v[42:45]
	s_waitcnt lgkmcnt(0)
	v_mfma_f32_16x16x32_bf16 v[38:41], v[148:151], v[98:101], v[38:41]
	v_mfma_f32_16x16x32_bf16 v[30:33], v[152:155], v[98:101], v[30:33]
	ds_read_b128 v[86:89], v77 offset:34112
	ds_read_b128 v[90:93], v77 offset:42560
	ds_read_b128 v[94:97], v77 offset:51008
	ds_read_b128 v[98:101], v77 offset:59456
	s_waitcnt lgkmcnt(3)
	v_mfma_f32_16x16x32_bf16 v[34:37], v[148:151], v[86:89], v[34:37]
	v_mfma_f32_16x16x32_bf16 v[26:29], v[152:155], v[86:89], v[26:29]
	s_waitcnt lgkmcnt(2)
	v_mfma_f32_16x16x32_bf16 v[22:25], v[148:151], v[90:93], v[22:25]
	v_mfma_f32_16x16x32_bf16 v[18:21], v[152:155], v[90:93], v[18:21]
	s_waitcnt lgkmcnt(1)
	v_mfma_f32_16x16x32_bf16 v[14:17], v[148:151], v[94:97], v[14:17]
	v_mfma_f32_16x16x32_bf16 v[2:5], v[152:155], v[94:97], v[2:5]
	s_waitcnt lgkmcnt(0)
	v_mfma_f32_16x16x32_bf16 v[10:13], v[148:151], v[98:101], v[10:13]
	v_mfma_f32_16x16x32_bf16 v[6:9], v[152:155], v[98:101], v[6:9]
	s_waitcnt vmcnt(2)
	ds_read_b128 v[86:89], v77 offset:384
	ds_read_b128 v[90:93], v77 offset:8832
	ds_read_b128 v[94:97], v77 offset:17280
	ds_read_b128 v[98:101], v77 offset:25728
	s_waitcnt lgkmcnt(3)
	v_mfma_f32_16x16x32_bf16 v[54:57], v[156:159], v[86:89], v[54:57]
	v_mfma_f32_16x16x32_bf16 v[58:61], v[160:163], v[86:89], v[58:61]
	s_waitcnt lgkmcnt(2)
	v_mfma_f32_16x16x32_bf16 v[68:71], v[156:159], v[90:93], v[68:71]
	v_mfma_f32_16x16x32_bf16 v[50:53], v[160:163], v[90:93], v[50:53]
	s_waitcnt lgkmcnt(1)
	v_mfma_f32_16x16x32_bf16 v[46:49], v[156:159], v[94:97], v[46:49]
	v_mfma_f32_16x16x32_bf16 v[42:45], v[160:163], v[94:97], v[42:45]
	s_waitcnt lgkmcnt(0)
	v_mfma_f32_16x16x32_bf16 v[38:41], v[156:159], v[98:101], v[38:41]
	v_mfma_f32_16x16x32_bf16 v[30:33], v[160:163], v[98:101], v[30:33]
	ds_read_b128 v[86:89], v77 offset:34176
	ds_read_b128 v[90:93], v77 offset:42624
	ds_read_b128 v[94:97], v77 offset:51072
	ds_read_b128 v[98:101], v77 offset:59520
	s_waitcnt lgkmcnt(3)
	v_mfma_f32_16x16x32_bf16 v[34:37], v[156:159], v[86:89], v[34:37]
	v_mfma_f32_16x16x32_bf16 v[26:29], v[160:163], v[86:89], v[26:29]
	s_waitcnt lgkmcnt(2)
	v_mfma_f32_16x16x32_bf16 v[22:25], v[156:159], v[90:93], v[22:25]
	v_mfma_f32_16x16x32_bf16 v[18:21], v[160:163], v[90:93], v[18:21]
	s_waitcnt lgkmcnt(1)
	v_mfma_f32_16x16x32_bf16 v[14:17], v[156:159], v[94:97], v[14:17]
	v_mfma_f32_16x16x32_bf16 v[2:5], v[160:163], v[94:97], v[2:5]
	s_waitcnt lgkmcnt(0)
	v_mfma_f32_16x16x32_bf16 v[10:13], v[156:159], v[98:101], v[10:13]
	v_mfma_f32_16x16x32_bf16 v[6:9], v[160:163], v[98:101], v[6:9]
	s_waitcnt vmcnt(0)
	ds_read_b128 v[86:89], v77 offset:448
	ds_read_b128 v[90:93], v77 offset:8896
	ds_read_b128 v[94:97], v77 offset:17344
	ds_read_b128 v[98:101], v77 offset:25792
	s_waitcnt lgkmcnt(3)
; DI unsigned pk2(float lo, float hi) { const f32x2 v = {lo, hi}; const bf16x2_t b = __builtin_convertvector(v, bf16x2_t); return __builtin_bit_cast(unsigned, b); }
; DI float bf2f(unsigned b) { return __uint_as_float(b << 16); }
; template <int NT2>
; DI void glu_prologue(const Params& p, char* lds, int l, int tile0, int tile1) {
;     ...
;     for (int ks = 0; ks < 8; ++ks) {
;         bf16x8 bb[2];
; #pragma unroll
;         for (int nt = 0; nt < 2; ++nt) bb[nt] = *(const bf16x8*)(Wg + (wid * 32 + nt * 16 + l15) * 256 + 32 * ks + 8 * quad);
; #pragma unroll
;         for (int tt = 0; tt < NT2; ++tt) {
;             const char* Ys = lds + tt * 33792;
;             bf16x8 a[4];
; #pragma unroll
;             for (int mt = 0; mt < 4; ++mt) a[mt] = *(const bf16x8*)(Ys + (mt * 16 + l15) * 528 + (32 * ks + 8 * quad) * 2);
; #pragma unroll
;             for (int mt = 0; mt < 4; ++mt)
; #pragma unroll
;                 for (int nt = 0; nt < 2; ++nt) acc[tt][mt][nt] = mfma16(bb[nt], a[mt], acc[tt][mt][nt]);
;         }
;     }
;     bf16_t* yo = WS_PTR(bf16_t, OFF_Y);
; #pragma unroll
;     for (int tt = 0; tt < NT2; ++tt) {
;         const int tile = tt ? tile1 : tile0;
;         const char* Ys = lds + tt * 33792;
;         const bf16_t* sg = WS_PTR(const bf16_t, OFF_SG) + (size_t)tile * 64 * 256;
; #pragma unroll
;         for (int mt = 0; mt < 4; ++mt) {
;             const int tok = mt * 16 + l15;
; #pragma unroll
;             for (int nt = 0; nt < 2; ++nt) {
;                 const int n0 = wid * 32 + nt * 16 + quad * 4;
;                 const f32x4 gb = *(const f32x4*)(p.glu_b + l * 256 + n0);
;                 const u32x2 yv = *(const u32x2*)(Ys + tok * 528 + n0 * 2);
;                 const u32x2 sv = *(const u32x2*)(sg + (size_t)tok * 256 + n0);
;                 float o[4];
;                 o[0] = sigmoid_f(acc[tt][mt][nt][0] + gb[0]) * bf2f(yv[0] & 0xffffu) * bf2f(sv[0] & 0xffffu);
;                 o[1] = sigmoid_f(acc[tt][mt][nt][1] + gb[1]) * bf2f(yv[0] >> 16) * bf2f(sv[0] >> 16);
;                 o[2] = sigmoid_f(acc[tt][mt][nt][2] + gb[2]) * bf2f(yv[1] & 0xffffu) * bf2f(sv[1] & 0xffffu);
;                 o[3] = sigmoid_f(acc[tt][mt][nt][3] + gb[3]) * bf2f(yv[1] >> 16) * bf2f(sv[1] >> 16);
;                 *(u32x2*)(yo + y_off(tile * 64 + tok, 512 + n0)) = (u32x2){pk2(o[0], o[1]), pk2(o[2], o[3])};
;             }
	v_mfma_f32_16x16x32_bf16 v[54:57], v[164:167], v[86:89], v[54:57]
	v_mfma_f32_16x16x32_bf16 v[58:61], v[168:171], v[86:89], v[58:61]
	s_waitcnt lgkmcnt(2)
	v_mfma_f32_16x16x32_bf16 v[68:71], v[164:167], v[90:93], v[68:71]
	v_mfma_f32_16x16x32_bf16 v[50:53], v[168:171], v[90:93], v[50:53]
	s_waitcnt lgkmcnt(1)
	v_mfma_f32_16x16x32_bf16 v[46:49], v[164:167], v[94:97], v[46:49]
	v_mfma_f32_16x16x32_bf16 v[42:45], v[168:171], v[94:97], v[42:45]
	s_waitcnt lgkmcnt(0)
	v_mfma_f32_16x16x32_bf16 v[38:41], v[164:167], v[98:101], v[38:41]
	v_mfma_f32_16x16x32_bf16 v[30:33], v[168:171], v[98:101], v[30:33]
	ds_read_b128 v[86:89], v77 offset:34240
	ds_read_b128 v[90:93], v77 offset:42688
	ds_read_b128 v[94:97], v77 offset:51136
	ds_read_b128 v[98:101], v77 offset:59584
	s_waitcnt lgkmcnt(3)
	v_mfma_f32_16x16x32_bf16 v[34:37], v[164:167], v[86:89], v[34:37]
	v_mfma_f32_16x16x32_bf16 v[26:29], v[168:171], v[86:89], v[26:29]
	s_waitcnt lgkmcnt(2)
	v_mfma_f32_16x16x32_bf16 v[22:25], v[164:167], v[90:93], v[22:25]
	v_mfma_f32_16x16x32_bf16 v[18:21], v[168:171], v[90:93], v[18:21]
	s_waitcnt lgkmcnt(1)
	v_mfma_f32_16x16x32_bf16 v[14:17], v[164:167], v[94:97], v[14:17]
	v_mfma_f32_16x16x32_bf16 v[2:5], v[168:171], v[94:97], v[2:5]
	s_waitcnt lgkmcnt(0)
	v_mfma_f32_16x16x32_bf16 v[10:13], v[164:167], v[98:101], v[10:13]
	v_mfma_f32_16x16x32_bf16 v[6:9], v[168:171], v[98:101], v[6:9]
	v_lshlrev_b32_e32 v66, 5, v76
	v_lshlrev_b32_e32 v62, 2, v79
	v_or_b32_e32 v62, v62, v66
	v_ashrrev_i32_e32 v63, 31, v62
	v_lshl_add_u64 v[76:77], v[62:63], 2, s[2:3]
	global_load_dwordx4 v[92:95], v[76:77], off
	v_readlane_b32 s40, v244, 48
	s_add_u32 s8, s40, s8
	v_readlane_b32 s46, v244, 49
	s_addc_u32 s9, s46, s9
	v_lshlrev_b32_e32 v0, 1, v0
	v_lshl_add_u64 v[96:97], s[8:9], 0, v[0:1]
	v_lshlrev_b64 v[80:81], 1, v[62:63]
	v_lshl_add_u64 v[64:65], v[96:97], 0, v[80:81]
	global_load_dwordx2 v[98:99], v[64:65], off
	v_and_b32_e32 v63, 0xffffffc0, v78
	v_add_u32_e32 v86, 0x400, v63
	v_lshl_add_u32 v89, s34, 11, v86
	v_add_u32_e32 v87, 0, v82
	v_or_b32_e32 v82, v89, v84
	v_ashrrev_i32_e32 v63, 31, v66
	v_ashrrev_i32_e32 v83, 31, v82
	v_lshlrev_b32_e32 v90, 1, v62
	v_lshl_add_u64 v[72:73], v[62:63], 2, s[2:3]
	v_lshlrev_b64 v[74:75], 1, v[62:63]
	v_lshlrev_b64 v[62:63], 6, v[82:83]
	v_add_u32_e32 v64, v87, v90
	ds_read2st64_b64 v[64:67], v64 offset1:66
	v_lshlrev_b32_e32 v78, 3, v79
	v_mov_b32_e32 v79, v1
	v_lshl_add_u64 v[62:63], s[54:55], 0, v[62:63]
	v_lshl_add_u64 v[100:101], v[62:63], 0, v[78:79]
	s_waitcnt lgkmcnt(0)
	v_lshlrev_b32_e32 v62, 16, v64
	v_and_b32_e32 v63, 0xffff0000, v64
	v_lshlrev_b32_e32 v64, 16, v65
	v_and_b32_e32 v65, 0xffff0000, v65
	v_add_u32_e32 v91, 0x2100, v87
	s_add_u32 s6, s40, s6
	s_addc_u32 s7, s46, s7
	s_waitcnt vmcnt(1)
	v_add_f32_e32 v54, v54, v92
	v_add_f32_e32 v55, v55, v93
	v_add_f32_e32 v56, v56, v94
	v_add_f32_e32 v57, v57, v95
	v_mul_f32_e32 v82, 0xbfb8aa3b, v54
	v_mul_f32_e32 v83, 0xbfb8aa3b, v55
	v_mul_f32_e32 v56, 0xbfb8aa3b, v56
	v_mul_f32_e32 v57, 0xbfb8aa3b, v57
	v_exp_f32_e32 v82, v82
	v_exp_f32_e32 v83, v83
	v_exp_f32_e32 v56, v56
	v_exp_f32_e32 v57, v57
	v_add_f32_e32 v82, 1.0, v82
	v_add_f32_e32 v83, 1.0, v83
	v_add_f32_e32 v85, 1.0, v56
	v_add_f32_e32 v88, 1.0, v57
	v_rcp_f32_e32 v56, v82
	v_rcp_f32_e32 v57, v83
	v_rcp_f32_e32 v82, v85
	v_rcp_f32_e32 v83, v88
	s_waitcnt vmcnt(0)
	v_lshlrev_b32_e32 v54, 16, v98
	v_and_b32_e32 v55, 0xffff0000, v98
	v_lshlrev_b32_e32 v92, 16, v99
	v_and_b32_e32 v93, 0xffff0000, v99
	v_pk_mul_f32 v[56:57], v[56:57], v[62:63]
	v_pk_mul_f32 v[62:63], v[82:83], v[64:65]
	v_pk_mul_f32 v[54:55], v[56:57], v[54:55]
	v_pk_mul_f32 v[56:57], v[62:63], v[92:93]
	v_cvt_pk_bf16_f32 v54, v54, v55
	v_cvt_pk_bf16_f32 v55, v56, v57
	global_store_dwordx2 v[100:101], v[54:55], off
	global_load_dwordx4 v[62:65], v[72:73], off offset:64
	v_lshl_add_u64 v[54:55], v[96:97], 0, v[74:75]
	global_load_dwordx2 v[92:93], v[54:55], off offset:32
	v_or_b32_e32 v88, 32, v90
	v_add_u32_e32 v54, v87, v88
	ds_read2st64_b64 v[54:57], v54 offset1:66
	v_or_b32_e32 v85, 16, v84
	v_mov_b32_e32 v83, v1
	v_lshlrev_b32_e32 v82, 9, v85
	v_lshl_add_u64 v[94:95], s[8:9], 0, v[82:83]
	s_waitcnt lgkmcnt(0)
	v_lshlrev_b32_e32 v96, 16, v54
	v_and_b32_e32 v97, 0xffff0000, v54
	v_lshlrev_b32_e32 v54, 16, v55
	v_and_b32_e32 v55, 0xffff0000, v55
	s_waitcnt vmcnt(1)
	v_add_f32_e32 v62, v58, v62
	v_add_f32_e32 v63, v59, v63
	v_add_f32_e32 v60, v60, v64
	v_add_f32_e32 v61, v61, v65
	v_mul_f32_e32 v62, 0xbfb8aa3b, v62
	v_mul_f32_e32 v63, 0xbfb8aa3b, v63
	v_mul_f32_e32 v60, 0xbfb8aa3b, v60
	v_mul_f32_e32 v61, 0xbfb8aa3b, v61
	v_exp_f32_e32 v62, v62
	v_exp_f32_e32 v63, v63
	v_exp_f32_e32 v60, v60
	v_exp_f32_e32 v61, v61
	v_add_f32_e32 v62, 1.0, v62
	v_add_f32_e32 v63, 1.0, v63
	v_add_f32_e32 v64, 1.0, v60
	v_add_f32_e32 v65, 1.0, v61
	v_rcp_f32_e32 v60, v62
	v_rcp_f32_e32 v61, v63
	v_rcp_f32_e32 v62, v64
	v_rcp_f32_e32 v63, v65
	s_waitcnt vmcnt(0)
	v_lshlrev_b32_e32 v58, 16, v92
	v_and_b32_e32 v59, 0xffff0000, v92
	v_lshlrev_b32_e32 v64, 16, v93
	v_and_b32_e32 v65, 0xffff0000, v93
	v_pk_mul_f32 v[60:61], v[60:61], v[96:97]
	v_pk_mul_f32 v[54:55], v[62:63], v[54:55]
	v_pk_mul_f32 v[58:59], v[60:61], v[58:59]
	v_pk_mul_f32 v[54:55], v[54:55], v[64:65]
	v_cvt_pk_bf16_f32 v58, v58, v59
	v_cvt_pk_bf16_f32 v59, v54, v55
	global_store_dwordx2 v[100:101], v[58:59], off offset:32
	v_lshl_add_u64 v[54:55], v[94:95], 0, v[80:81]
	global_load_dwordx4 v[62:65], v[76:77], off
	v_add_u32_e32 v58, v91, v90
	global_load_dwordx2 v[54:55], v[54:55], off
	ds_read2st64_b64 v[58:61], v58 offset1:66
	v_or_b32_e32 v92, v89, v85
	v_ashrrev_i32_e32 v93, 31, v92
	v_lshlrev_b64 v[92:93], 6, v[92:93]
	v_lshl_add_u64 v[92:93], s[54:55], 0, v[92:93]
	s_waitcnt lgkmcnt(0)
; DI unsigned pk2(float lo, float hi) { const f32x2 v = {lo, hi}; const bf16x2_t b = __builtin_convertvector(v, bf16x2_t); return __builtin_bit_cast(unsigned, b); }
; DI float bf2f(unsigned b) { return __uint_as_float(b << 16); }
; DI float sigmoid_f(float x) { return __builtin_amdgcn_rcpf(1.f + __builtin_amdgcn_exp2f(x * -1.44269504089f)); }
; DI size_t y_off(int tok, int col) { return ((size_t)(((tok >> 6) * 32 + (col >> 5)) * 64 + (tok & 63))) * 32 + (col & 31); }
; template <int NT2>
; DI void glu_prologue(const Params& p, char* lds, int l, int tile0, int tile1) {
;     ...
; #pragma unroll
;         for (int mt = 0; mt < 4; ++mt) {
;             const int tok = mt * 16 + l15;
; #pragma unroll
;             for (int nt = 0; nt < 2; ++nt) {
;                 const int n0 = wid * 32 + nt * 16 + quad * 4;
;                 const f32x4 gb = *(const f32x4*)(p.glu_b + l * 256 + n0);
;                 const u32x2 yv = *(const u32x2*)(Ys + tok * 528 + n0 * 2);
;                 const u32x2 sv = *(const u32x2*)(sg + (size_t)tok * 256 + n0);
;                 float o[4];
;                 o[0] = sigmoid_f(acc[tt][mt][nt][0] + gb[0]) * bf2f(yv[0] & 0xffffu) * bf2f(sv[0] & 0xffffu);
;                 o[1] = sigmoid_f(acc[tt][mt][nt][1] + gb[1]) * bf2f(yv[0] >> 16) * bf2f(sv[0] >> 16);
;                 o[2] = sigmoid_f(acc[tt][mt][nt][2] + gb[2]) * bf2f(yv[1] & 0xffffu) * bf2f(sv[1] & 0xffffu);
;                 o[3] = sigmoid_f(acc[tt][mt][nt][3] + gb[3]) * bf2f(yv[1] >> 16) * bf2f(sv[1] >> 16);
;                 *(u32x2*)(yo + y_off(tile * 64 + tok, 512 + n0)) = (u32x2){pk2(o[0], o[1]), pk2(o[2], o[3])};
;             }
	v_lshlrev_b32_e32 v96, 16, v58
	v_and_b32_e32 v97, 0xffff0000, v58
	v_lshlrev_b32_e32 v58, 16, v59
	v_and_b32_e32 v59, 0xffff0000, v59
	v_lshl_add_u64 v[92:93], v[92:93], 0, v[78:79]
	s_waitcnt vmcnt(1)
	v_add_f32_e32 v68, v68, v62
	v_add_f32_e32 v69, v69, v63
	s_waitcnt vmcnt(0)
	v_lshlrev_b32_e32 v62, 16, v54
	v_and_b32_e32 v63, 0xffff0000, v54
	v_add_f32_e32 v54, v70, v64
	v_add_f32_e32 v64, v71, v65
	v_mul_f32_e32 v65, 0xbfb8aa3b, v68
	v_mul_f32_e32 v68, 0xbfb8aa3b, v69
	v_mul_f32_e32 v54, 0xbfb8aa3b, v54
	v_mul_f32_e32 v64, 0xbfb8aa3b, v64
	v_exp_f32_e32 v65, v65
	v_exp_f32_e32 v68, v68
	v_exp_f32_e32 v54, v54
	v_exp_f32_e32 v64, v64
	v_add_f32_e32 v65, 1.0, v65
	v_add_f32_e32 v68, 1.0, v68
	v_add_f32_e32 v54, 1.0, v54
	v_add_f32_e32 v69, 1.0, v64
	v_rcp_f32_e32 v64, v65
	v_rcp_f32_e32 v65, v68
	v_rcp_f32_e32 v68, v54
	v_rcp_f32_e32 v69, v69
	v_lshlrev_b32_e32 v54, 16, v55
	v_and_b32_e32 v55, 0xffff0000, v55
	v_pk_mul_f32 v[64:65], v[64:65], v[96:97]
	v_pk_mul_f32 v[58:59], v[68:69], v[58:59]
	v_pk_mul_f32 v[62:63], v[64:65], v[62:63]
	v_pk_mul_f32 v[54:55], v[58:59], v[54:55]
	v_cvt_pk_bf16_f32 v58, v62, v63
	v_cvt_pk_bf16_f32 v59, v54, v55
	global_store_dwordx2 v[92:93], v[58:59], off
	global_load_dwordx4 v[68:71], v[72:73], off offset:64
	v_lshl_add_u64 v[54:55], v[94:95], 0, v[74:75]
	global_load_dwordx2 v[94:95], v[54:55], off offset:32
	v_add_u32_e32 v54, v91, v88
	ds_read2st64_b64 v[62:65], v54 offset1:66
	v_or_b32_e32 v58, 32, v84
	v_mov_b32_e32 v55, v1
	v_lshlrev_b32_e32 v54, 9, v58
	v_lshl_add_u64 v[96:97], s[8:9], 0, v[54:55]
	s_waitcnt lgkmcnt(0)
	v_lshlrev_b32_e32 v98, 16, v62
	v_and_b32_e32 v99, 0xffff0000, v62
	v_lshlrev_b32_e32 v62, 16, v63
	v_and_b32_e32 v63, 0xffff0000, v63
	s_waitcnt vmcnt(1)
	v_add_f32_e32 v59, v50, v68
	v_add_f32_e32 v68, v51, v69
	v_add_f32_e32 v52, v52, v70
	v_add_f32_e32 v53, v53, v71
	v_mul_f32_e32 v59, 0xbfb8aa3b, v59
	v_mul_f32_e32 v68, 0xbfb8aa3b, v68
	v_mul_f32_e32 v52, 0xbfb8aa3b, v52
	v_mul_f32_e32 v53, 0xbfb8aa3b, v53
	v_exp_f32_e32 v59, v59
	v_exp_f32_e32 v68, v68
	v_exp_f32_e32 v52, v52
	v_exp_f32_e32 v53, v53
	v_add_f32_e32 v59, 1.0, v59
	v_add_f32_e32 v68, 1.0, v68
	v_add_f32_e32 v69, 1.0, v52
	v_add_f32_e32 v70, 1.0, v53
	v_rcp_f32_e32 v52, v59
	v_rcp_f32_e32 v53, v68
	v_rcp_f32_e32 v68, v69
	v_rcp_f32_e32 v69, v70
	s_waitcnt vmcnt(0)
	v_lshlrev_b32_e32 v50, 16, v94
	v_and_b32_e32 v51, 0xffff0000, v94
	v_lshlrev_b32_e32 v70, 16, v95
	v_and_b32_e32 v71, 0xffff0000, v95
	v_pk_mul_f32 v[52:53], v[52:53], v[98:99]
	v_pk_mul_f32 v[62:63], v[68:69], v[62:63]
	v_pk_mul_f32 v[50:51], v[52:53], v[50:51]
	v_pk_mul_f32 v[52:53], v[62:63], v[70:71]
	v_cvt_pk_bf16_f32 v50, v50, v51
	v_cvt_pk_bf16_f32 v51, v52, v53
	global_store_dwordx2 v[92:93], v[50:51], off offset:32
	global_load_dwordx4 v[68:71], v[76:77], off
	v_lshl_add_u64 v[50:51], v[96:97], 0, v[80:81]
	global_load_dwordx2 v[62:63], v[50:51], off
	v_add_u32_e32 v59, 0x4200, v87
	v_add_u32_e32 v50, v59, v90
	ds_read2st64_b64 v[50:53], v50 offset1:66
	v_or_b32_e32 v92, v89, v58
	v_ashrrev_i32_e32 v93, 31, v92
	v_lshlrev_b64 v[92:93], 6, v[92:93]
	v_lshl_add_u64 v[92:93], s[54:55], 0, v[92:93]
	s_waitcnt lgkmcnt(0)
	v_lshlrev_b32_e32 v94, 16, v50
	v_and_b32_e32 v95, 0xffff0000, v50
	v_lshlrev_b32_e32 v50, 16, v51
	v_and_b32_e32 v51, 0xffff0000, v51
	v_lshl_add_u64 v[92:93], v[92:93], 0, v[78:79]
	v_add_u32_e32 v87, 0x6300, v87
	s_waitcnt vmcnt(1)
	v_add_f32_e32 v68, v46, v68
	v_add_f32_e32 v69, v47, v69
	v_add_f32_e32 v48, v48, v70
	v_add_f32_e32 v49, v49, v71
	s_waitcnt vmcnt(0)
	v_lshlrev_b32_e32 v46, 16, v62
	v_and_b32_e32 v47, 0xffff0000, v62
	v_mul_f32_e32 v62, 0xbfb8aa3b, v68
	v_mul_f32_e32 v68, 0xbfb8aa3b, v69
	v_mul_f32_e32 v48, 0xbfb8aa3b, v48
	v_mul_f32_e32 v49, 0xbfb8aa3b, v49
	v_exp_f32_e32 v62, v62
	v_exp_f32_e32 v68, v68
	v_exp_f32_e32 v48, v48
	v_exp_f32_e32 v49, v49
	v_add_f32_e32 v62, 1.0, v62
	v_add_f32_e32 v68, 1.0, v68
	v_add_f32_e32 v69, 1.0, v48
	v_add_f32_e32 v70, 1.0, v49
	v_rcp_f32_e32 v48, v62
	v_rcp_f32_e32 v49, v68
	v_rcp_f32_e32 v68, v69
	v_rcp_f32_e32 v69, v70
	v_lshlrev_b32_e32 v62, 16, v63
	v_and_b32_e32 v63, 0xffff0000, v63
	v_pk_mul_f32 v[48:49], v[48:49], v[94:95]
	v_pk_mul_f32 v[50:51], v[68:69], v[50:51]
	v_pk_mul_f32 v[46:47], v[48:49], v[46:47]
	v_pk_mul_f32 v[48:49], v[50:51], v[62:63]
	v_cvt_pk_bf16_f32 v46, v46, v47
	v_cvt_pk_bf16_f32 v47, v48, v49
	global_store_dwordx2 v[92:93], v[46:47], off
	global_load_dwordx4 v[68:71], v[72:73], off offset:64
	v_lshl_add_u64 v[46:47], v[96:97], 0, v[74:75]
	global_load_dwordx2 v[62:63], v[46:47], off offset:32
	v_add_u32_e32 v46, v59, v88
	ds_read2st64_b64 v[46:49], v46 offset1:66
	v_or_b32_e32 v59, 48, v84
	v_mov_b32_e32 v51, v1
	v_lshlrev_b32_e32 v50, 9, v59
	v_lshl_add_u64 v[94:95], s[8:9], 0, v[50:51]
	s_waitcnt lgkmcnt(0)
	v_lshlrev_b32_e32 v96, 16, v46
	v_and_b32_e32 v97, 0xffff0000, v46
	v_lshlrev_b32_e32 v46, 16, v47
	v_and_b32_e32 v47, 0xffff0000, v47
	s_waitcnt vmcnt(1)
	v_add_f32_e32 v68, v42, v68
	v_add_f32_e32 v69, v43, v69
	v_add_f32_e32 v44, v44, v70
	v_add_f32_e32 v45, v45, v71
	s_waitcnt vmcnt(0)
; DI unsigned pk2(float lo, float hi) { const f32x2 v = {lo, hi}; const bf16x2_t b = __builtin_convertvector(v, bf16x2_t); return __builtin_bit_cast(unsigned, b); }
; DI float bf2f(unsigned b) { return __uint_as_float(b << 16); }
; DI float sigmoid_f(float x) { return __builtin_amdgcn_rcpf(1.f + __builtin_amdgcn_exp2f(x * -1.44269504089f)); }
; DI size_t y_off(int tok, int col) { return ((size_t)(((tok >> 6) * 32 + (col >> 5)) * 64 + (tok & 63))) * 32 + (col & 31); }
; template <int NT2>
; DI void glu_prologue(const Params& p, char* lds, int l, int tile0, int tile1) {
;     ...
; #pragma unroll
;         for (int mt = 0; mt < 4; ++mt) {
;             const int tok = mt * 16 + l15;
; #pragma unroll
;             for (int nt = 0; nt < 2; ++nt) {
;                 const int n0 = wid * 32 + nt * 16 + quad * 4;
;                 const f32x4 gb = *(const f32x4*)(p.glu_b + l * 256 + n0);
;                 const u32x2 yv = *(const u32x2*)(Ys + tok * 528 + n0 * 2);
;                 const u32x2 sv = *(const u32x2*)(sg + (size_t)tok * 256 + n0);
;                 float o[4];
;                 o[0] = sigmoid_f(acc[tt][mt][nt][0] + gb[0]) * bf2f(yv[0] & 0xffffu) * bf2f(sv[0] & 0xffffu);
;                 o[1] = sigmoid_f(acc[tt][mt][nt][1] + gb[1]) * bf2f(yv[0] >> 16) * bf2f(sv[0] >> 16);
;                 o[2] = sigmoid_f(acc[tt][mt][nt][2] + gb[2]) * bf2f(yv[1] & 0xffffu) * bf2f(sv[1] & 0xffffu);
;                 o[3] = sigmoid_f(acc[tt][mt][nt][3] + gb[3]) * bf2f(yv[1] >> 16) * bf2f(sv[1] >> 16);
;                 *(u32x2*)(yo + y_off(tile * 64 + tok, 512 + n0)) = (u32x2){pk2(o[0], o[1]), pk2(o[2], o[3])};
;             }
	v_lshlrev_b32_e32 v42, 16, v62
	v_and_b32_e32 v43, 0xffff0000, v62
	v_mul_f32_e32 v62, 0xbfb8aa3b, v68
	v_mul_f32_e32 v68, 0xbfb8aa3b, v69
	v_mul_f32_e32 v44, 0xbfb8aa3b, v44
	v_mul_f32_e32 v45, 0xbfb8aa3b, v45
	v_exp_f32_e32 v62, v62
	v_exp_f32_e32 v68, v68
	v_exp_f32_e32 v44, v44
	v_exp_f32_e32 v45, v45
	v_add_f32_e32 v62, 1.0, v62
	v_add_f32_e32 v68, 1.0, v68
	v_add_f32_e32 v69, 1.0, v44
	v_add_f32_e32 v70, 1.0, v45
	v_rcp_f32_e32 v44, v62
	v_rcp_f32_e32 v45, v68
	v_rcp_f32_e32 v68, v69
	v_rcp_f32_e32 v69, v70
	v_lshlrev_b32_e32 v62, 16, v63
	v_and_b32_e32 v63, 0xffff0000, v63
	v_pk_mul_f32 v[44:45], v[44:45], v[96:97]
	v_pk_mul_f32 v[46:47], v[68:69], v[46:47]
	v_pk_mul_f32 v[42:43], v[44:45], v[42:43]
	v_pk_mul_f32 v[44:45], v[46:47], v[62:63]
	v_cvt_pk_bf16_f32 v42, v42, v43
	v_cvt_pk_bf16_f32 v43, v44, v45
	global_store_dwordx2 v[92:93], v[42:43], off offset:32
	global_load_dwordx4 v[68:71], v[76:77], off
	v_lshl_add_u64 v[42:43], v[94:95], 0, v[80:81]
	global_load_dwordx2 v[46:47], v[42:43], off
	v_add_u32_e32 v42, v87, v90
	ds_read2st64_b64 v[42:45], v42 offset1:66
	v_or_b32_e32 v62, v89, v59
	v_ashrrev_i32_e32 v63, 31, v62
	v_lshlrev_b64 v[62:63], 6, v[62:63]
	v_lshl_add_u64 v[62:63], s[54:55], 0, v[62:63]
	s_waitcnt lgkmcnt(0)
	v_lshlrev_b32_e32 v90, 16, v42
	v_and_b32_e32 v91, 0xffff0000, v42
	v_lshlrev_b32_e32 v42, 16, v43
	v_and_b32_e32 v43, 0xffff0000, v43
	v_lshl_add_u64 v[62:63], v[62:63], 0, v[78:79]
	s_waitcnt vmcnt(1)
	v_add_f32_e32 v68, v38, v68
	v_add_f32_e32 v69, v39, v69
	v_add_f32_e32 v40, v40, v70
	v_add_f32_e32 v41, v41, v71
	s_waitcnt vmcnt(0)
	v_lshlrev_b32_e32 v38, 16, v46
	v_and_b32_e32 v39, 0xffff0000, v46
	v_mul_f32_e32 v46, 0xbfb8aa3b, v68
	v_mul_f32_e32 v68, 0xbfb8aa3b, v69
	v_mul_f32_e32 v40, 0xbfb8aa3b, v40
	v_mul_f32_e32 v41, 0xbfb8aa3b, v41
	v_exp_f32_e32 v46, v46
	v_exp_f32_e32 v68, v68
	v_exp_f32_e32 v40, v40
	v_exp_f32_e32 v41, v41
	v_add_f32_e32 v46, 1.0, v46
	v_add_f32_e32 v68, 1.0, v68
	v_add_f32_e32 v69, 1.0, v40
	v_add_f32_e32 v70, 1.0, v41
	v_rcp_f32_e32 v40, v46
	v_rcp_f32_e32 v41, v68
	v_rcp_f32_e32 v68, v69
	v_rcp_f32_e32 v69, v70
	v_lshlrev_b32_e32 v46, 16, v47
	v_and_b32_e32 v47, 0xffff0000, v47
	v_pk_mul_f32 v[40:41], v[40:41], v[90:91]
	v_pk_mul_f32 v[42:43], v[68:69], v[42:43]
	v_pk_mul_f32 v[38:39], v[40:41], v[38:39]
	v_pk_mul_f32 v[40:41], v[42:43], v[46:47]
	v_cvt_pk_bf16_f32 v38, v38, v39
	v_cvt_pk_bf16_f32 v39, v40, v41
	global_store_dwordx2 v[62:63], v[38:39], off
	global_load_dwordx4 v[68:71], v[72:73], off offset:64
	v_lshl_add_u64 v[38:39], v[94:95], 0, v[74:75]
	global_load_dwordx2 v[42:43], v[38:39], off offset:32
	v_lshl_add_u64 v[46:47], s[6:7], 0, v[0:1]
	v_add_u32_e32 v38, v87, v88
	ds_read2st64_b64 v[38:41], v38 offset1:66
	s_waitcnt lgkmcnt(0)
	v_lshlrev_b32_e32 v88, 16, v38
	v_and_b32_e32 v89, 0xffff0000, v38
	v_lshlrev_b32_e32 v38, 16, v39
	v_and_b32_e32 v39, 0xffff0000, v39
	s_waitcnt vmcnt(1)
	v_add_f32_e32 v0, v30, v68
	v_add_f32_e32 v68, v31, v69
	v_add_f32_e32 v32, v32, v70
	v_add_f32_e32 v33, v33, v71
	s_waitcnt vmcnt(0)
	v_lshlrev_b32_e32 v30, 16, v42
	v_and_b32_e32 v31, 0xffff0000, v42
	v_mul_f32_e32 v0, 0xbfb8aa3b, v0
	v_mul_f32_e32 v42, 0xbfb8aa3b, v68
	v_mul_f32_e32 v32, 0xbfb8aa3b, v32
	v_mul_f32_e32 v33, 0xbfb8aa3b, v33
	v_exp_f32_e32 v0, v0
	v_exp_f32_e32 v42, v42
	v_exp_f32_e32 v32, v32
	v_exp_f32_e32 v33, v33
	v_add_f32_e32 v0, 1.0, v0
	v_add_f32_e32 v42, 1.0, v42
	v_add_f32_e32 v68, 1.0, v32
	v_add_f32_e32 v69, 1.0, v33
	v_rcp_f32_e32 v32, v0
	v_rcp_f32_e32 v33, v42
	v_rcp_f32_e32 v68, v68
	v_rcp_f32_e32 v69, v69
	v_lshlrev_b32_e32 v42, 16, v43
	v_and_b32_e32 v43, 0xffff0000, v43
	v_pk_mul_f32 v[32:33], v[32:33], v[88:89]
	v_pk_mul_f32 v[38:39], v[68:69], v[38:39]
	v_pk_mul_f32 v[30:31], v[32:33], v[30:31]
	v_pk_mul_f32 v[32:33], v[38:39], v[42:43]
	v_cvt_pk_bf16_f32 v30, v30, v31
	v_cvt_pk_bf16_f32 v31, v32, v33
	global_store_dwordx2 v[62:63], v[30:31], off offset:32
	global_load_dwordx4 v[30:33], v[76:77], off
	v_lshl_add_u64 v[38:39], v[46:47], 0, v[80:81]
	global_load_dwordx2 v[38:39], v[38:39], off
	v_lshl_add_u32 v0, s48, 11, v86
	v_or_b32_e32 v42, v0, v84
	v_ashrrev_i32_e32 v43, 31, v42
	v_lshlrev_b32_e32 v62, 16, v66
	v_and_b32_e32 v63, 0xffff0000, v66
	v_lshlrev_b32_e32 v66, 16, v67
	v_and_b32_e32 v67, 0xffff0000, v67
	v_lshlrev_b64 v[42:43], 6, v[42:43]
	v_lshl_add_u64 v[42:43], s[54:55], 0, v[42:43]
	v_lshl_add_u64 v[42:43], v[42:43], 0, v[78:79]
	s_waitcnt vmcnt(1)
	v_add_f32_e32 v34, v34, v30
	v_add_f32_e32 v35, v35, v31
	v_add_f32_e32 v32, v36, v32
	v_add_f32_e32 v33, v37, v33
	v_mul_f32_e32 v34, 0xbfb8aa3b, v34
	v_mul_f32_e32 v35, 0xbfb8aa3b, v35
	v_mul_f32_e32 v32, 0xbfb8aa3b, v32
	v_mul_f32_e32 v33, 0xbfb8aa3b, v33
	v_exp_f32_e32 v34, v34
	v_exp_f32_e32 v35, v35
	v_exp_f32_e32 v32, v32
	v_exp_f32_e32 v33, v33
	v_add_f32_e32 v34, 1.0, v34
	v_add_f32_e32 v35, 1.0, v35
	v_add_f32_e32 v36, 1.0, v32
	v_add_f32_e32 v37, 1.0, v33
	v_rcp_f32_e32 v32, v34
	v_rcp_f32_e32 v33, v35
	v_rcp_f32_e32 v34, v36
	v_rcp_f32_e32 v35, v37
	s_waitcnt vmcnt(0)
	v_lshlrev_b32_e32 v30, 16, v38
	v_and_b32_e32 v31, 0xffff0000, v38
	v_lshlrev_b32_e32 v36, 16, v39
	v_and_b32_e32 v37, 0xffff0000, v39
	v_pk_mul_f32 v[32:33], v[32:33], v[62:63]
	v_pk_mul_f32 v[34:35], v[34:35], v[66:67]
	v_pk_mul_f32 v[30:31], v[32:33], v[30:31]
	v_pk_mul_f32 v[32:33], v[34:35], v[36:37]
	v_cvt_pk_bf16_f32 v30, v30, v31
	v_cvt_pk_bf16_f32 v31, v32, v33
	global_store_dwordx2 v[42:43], v[30:31], off
	global_load_dwordx4 v[30:33], v[72:73], off offset:64
	v_lshl_add_u64 v[34:35], v[46:47], 0, v[74:75]
	global_load_dwordx2 v[34:35], v[34:35], off offset:32
	v_lshlrev_b32_e32 v38, 16, v56
	v_and_b32_e32 v39, 0xffff0000, v56
	v_lshlrev_b32_e32 v46, 16, v57
	v_and_b32_e32 v47, 0xffff0000, v57
	v_lshl_add_u64 v[36:37], s[6:7], 0, v[82:83]
	s_waitcnt vmcnt(1)
; DI unsigned pk2(float lo, float hi) { const f32x2 v = {lo, hi}; const bf16x2_t b = __builtin_convertvector(v, bf16x2_t); return __builtin_bit_cast(unsigned, b); }
; DI float bf2f(unsigned b) { return __uint_as_float(b << 16); }
; DI float sigmoid_f(float x) { return __builtin_amdgcn_rcpf(1.f + __builtin_amdgcn_exp2f(x * -1.44269504089f)); }
; DI size_t y_off(int tok, int col) { return ((size_t)(((tok >> 6) * 32 + (col >> 5)) * 64 + (tok & 63))) * 32 + (col & 31); }
; template <int NT2>
; DI void glu_prologue(const Params& p, char* lds, int l, int tile0, int tile1) {
;     ...
; #pragma unroll
;         for (int mt = 0; mt < 4; ++mt) {
;             const int tok = mt * 16 + l15;
; #pragma unroll
;             for (int nt = 0; nt < 2; ++nt) {
;                 const int n0 = wid * 32 + nt * 16 + quad * 4;
;                 const f32x4 gb = *(const f32x4*)(p.glu_b + l * 256 + n0);
;                 const u32x2 yv = *(const u32x2*)(Ys + tok * 528 + n0 * 2);
;                 const u32x2 sv = *(const u32x2*)(sg + (size_t)tok * 256 + n0);
;                 float o[4];
;                 o[0] = sigmoid_f(acc[tt][mt][nt][0] + gb[0]) * bf2f(yv[0] & 0xffffu) * bf2f(sv[0] & 0xffffu);
;                 o[1] = sigmoid_f(acc[tt][mt][nt][1] + gb[1]) * bf2f(yv[0] >> 16) * bf2f(sv[0] >> 16);
;                 o[2] = sigmoid_f(acc[tt][mt][nt][2] + gb[2]) * bf2f(yv[1] & 0xffffu) * bf2f(sv[1] & 0xffffu);
;                 o[3] = sigmoid_f(acc[tt][mt][nt][3] + gb[3]) * bf2f(yv[1] >> 16) * bf2f(sv[1] >> 16);
;                 *(u32x2*)(yo + y_off(tile * 64 + tok, 512 + n0)) = (u32x2){pk2(o[0], o[1]), pk2(o[2], o[3])};
;             }
	v_add_f32_e32 v30, v26, v30
	v_add_f32_e32 v31, v27, v31
	v_add_f32_e32 v28, v28, v32
	v_add_f32_e32 v29, v29, v33
	v_mul_f32_e32 v30, 0xbfb8aa3b, v30
	v_mul_f32_e32 v31, 0xbfb8aa3b, v31
	v_mul_f32_e32 v28, 0xbfb8aa3b, v28
	v_mul_f32_e32 v29, 0xbfb8aa3b, v29
	v_exp_f32_e32 v30, v30
	v_exp_f32_e32 v31, v31
	v_exp_f32_e32 v28, v28
	v_exp_f32_e32 v29, v29
	v_add_f32_e32 v30, 1.0, v30
	v_add_f32_e32 v31, 1.0, v31
	v_add_f32_e32 v32, 1.0, v28
	v_add_f32_e32 v33, 1.0, v29
	v_rcp_f32_e32 v28, v30
	v_rcp_f32_e32 v29, v31
	v_rcp_f32_e32 v30, v32
	v_rcp_f32_e32 v31, v33
	s_waitcnt vmcnt(0)
	v_lshlrev_b32_e32 v26, 16, v34
	v_and_b32_e32 v27, 0xffff0000, v34
	v_lshlrev_b32_e32 v32, 16, v35
	v_and_b32_e32 v33, 0xffff0000, v35
	v_pk_mul_f32 v[28:29], v[28:29], v[38:39]
	v_pk_mul_f32 v[30:31], v[30:31], v[46:47]
	v_pk_mul_f32 v[26:27], v[28:29], v[26:27]
	v_pk_mul_f32 v[28:29], v[30:31], v[32:33]
	v_cvt_pk_bf16_f32 v26, v26, v27
	v_cvt_pk_bf16_f32 v27, v28, v29
	global_store_dwordx2 v[42:43], v[26:27], off offset:32
	global_load_dwordx4 v[26:29], v[76:77], off
	v_lshl_add_u64 v[30:31], v[36:37], 0, v[80:81]
	global_load_dwordx2 v[30:31], v[30:31], off
	v_or_b32_e32 v32, v0, v85
	v_ashrrev_i32_e32 v33, 31, v32
	v_lshlrev_b32_e32 v34, 16, v60
	v_and_b32_e32 v35, 0xffff0000, v60
	v_lshlrev_b32_e32 v38, 16, v61
	v_and_b32_e32 v39, 0xffff0000, v61
	v_lshlrev_b64 v[32:33], 6, v[32:33]
	v_lshl_add_u64 v[32:33], s[54:55], 0, v[32:33]
	v_lshl_add_u64 v[32:33], v[32:33], 0, v[78:79]
	s_waitcnt vmcnt(1)
	v_add_f32_e32 v26, v22, v26
	v_add_f32_e32 v27, v23, v27
	v_add_f32_e32 v24, v24, v28
	v_add_f32_e32 v25, v25, v29
	v_mul_f32_e32 v26, 0xbfb8aa3b, v26
	v_mul_f32_e32 v27, 0xbfb8aa3b, v27
	v_mul_f32_e32 v24, 0xbfb8aa3b, v24
	v_mul_f32_e32 v25, 0xbfb8aa3b, v25
	v_exp_f32_e32 v26, v26
	v_exp_f32_e32 v27, v27
	v_exp_f32_e32 v24, v24
	v_exp_f32_e32 v25, v25
	v_add_f32_e32 v26, 1.0, v26
	v_add_f32_e32 v27, 1.0, v27
	v_add_f32_e32 v28, 1.0, v24
	v_add_f32_e32 v29, 1.0, v25
	v_rcp_f32_e32 v24, v26
	v_rcp_f32_e32 v25, v27
	v_rcp_f32_e32 v26, v28
	v_rcp_f32_e32 v27, v29
	s_waitcnt vmcnt(0)
	v_lshlrev_b32_e32 v22, 16, v30
	v_and_b32_e32 v23, 0xffff0000, v30
	v_lshlrev_b32_e32 v28, 16, v31
	v_and_b32_e32 v29, 0xffff0000, v31
	v_pk_mul_f32 v[24:25], v[24:25], v[34:35]
	v_pk_mul_f32 v[26:27], v[26:27], v[38:39]
	v_pk_mul_f32 v[22:23], v[24:25], v[22:23]
	v_pk_mul_f32 v[24:25], v[26:27], v[28:29]
	v_cvt_pk_bf16_f32 v22, v22, v23
	v_cvt_pk_bf16_f32 v23, v24, v25
	global_store_dwordx2 v[32:33], v[22:23], off
	global_load_dwordx4 v[22:25], v[72:73], off offset:64
	v_lshl_add_u64 v[26:27], v[36:37], 0, v[74:75]
	global_load_dwordx2 v[26:27], v[26:27], off offset:32
	v_lshlrev_b32_e32 v30, 16, v64
	v_and_b32_e32 v31, 0xffff0000, v64
	v_lshlrev_b32_e32 v34, 16, v65
	v_and_b32_e32 v35, 0xffff0000, v65
	v_lshl_add_u64 v[28:29], s[6:7], 0, v[54:55]
	s_waitcnt vmcnt(1)
	v_add_f32_e32 v22, v18, v22
	v_add_f32_e32 v23, v19, v23
	v_add_f32_e32 v20, v20, v24
	v_add_f32_e32 v21, v21, v25
	v_mul_f32_e32 v22, 0xbfb8aa3b, v22
	v_mul_f32_e32 v23, 0xbfb8aa3b, v23
	v_mul_f32_e32 v20, 0xbfb8aa3b, v20
	v_mul_f32_e32 v21, 0xbfb8aa3b, v21
	v_exp_f32_e32 v22, v22
	v_exp_f32_e32 v23, v23
	v_exp_f32_e32 v20, v20
	v_exp_f32_e32 v21, v21
	v_add_f32_e32 v22, 1.0, v22
	v_add_f32_e32 v23, 1.0, v23
	v_add_f32_e32 v24, 1.0, v20
	v_add_f32_e32 v25, 1.0, v21
	v_rcp_f32_e32 v20, v22
	v_rcp_f32_e32 v21, v23
	v_rcp_f32_e32 v22, v24
	v_rcp_f32_e32 v23, v25
	s_waitcnt vmcnt(0)
	v_lshlrev_b32_e32 v18, 16, v26
	v_and_b32_e32 v19, 0xffff0000, v26
	v_lshlrev_b32_e32 v24, 16, v27
	v_and_b32_e32 v25, 0xffff0000, v27
	v_pk_mul_f32 v[20:21], v[20:21], v[30:31]
	v_pk_mul_f32 v[22:23], v[22:23], v[34:35]
	v_pk_mul_f32 v[18:19], v[20:21], v[18:19]
	v_pk_mul_f32 v[20:21], v[22:23], v[24:25]
	v_cvt_pk_bf16_f32 v18, v18, v19
	v_cvt_pk_bf16_f32 v19, v20, v21
	global_store_dwordx2 v[32:33], v[18:19], off offset:32
	global_load_dwordx4 v[18:21], v[76:77], off
	v_lshl_add_u64 v[22:23], v[28:29], 0, v[80:81]
	global_load_dwordx2 v[22:23], v[22:23], off
	v_or_b32_e32 v24, v0, v58
	v_ashrrev_i32_e32 v25, 31, v24
	v_lshlrev_b32_e32 v26, 16, v52
	v_and_b32_e32 v27, 0xffff0000, v52
	v_lshlrev_b32_e32 v30, 16, v53
	v_and_b32_e32 v31, 0xffff0000, v53
	v_lshlrev_b64 v[24:25], 6, v[24:25]
	v_lshl_add_u64 v[24:25], s[54:55], 0, v[24:25]
	v_lshl_add_u64 v[24:25], v[24:25], 0, v[78:79]
	s_waitcnt vmcnt(1)
	v_add_f32_e32 v18, v14, v18
	v_add_f32_e32 v19, v15, v19
	v_add_f32_e32 v16, v16, v20
	v_add_f32_e32 v17, v17, v21
	v_mul_f32_e32 v18, 0xbfb8aa3b, v18
	v_mul_f32_e32 v19, 0xbfb8aa3b, v19
	v_mul_f32_e32 v16, 0xbfb8aa3b, v16
	v_mul_f32_e32 v17, 0xbfb8aa3b, v17
	v_exp_f32_e32 v18, v18
	v_exp_f32_e32 v19, v19
	v_exp_f32_e32 v16, v16
	v_exp_f32_e32 v17, v17
	v_add_f32_e32 v18, 1.0, v18
	v_add_f32_e32 v19, 1.0, v19
	v_add_f32_e32 v20, 1.0, v16
	v_add_f32_e32 v21, 1.0, v17
	v_rcp_f32_e32 v16, v18
	v_rcp_f32_e32 v17, v19
	v_rcp_f32_e32 v18, v20
	v_rcp_f32_e32 v19, v21
	s_waitcnt vmcnt(0)
; DI unsigned pk2(float lo, float hi) { const f32x2 v = {lo, hi}; const bf16x2_t b = __builtin_convertvector(v, bf16x2_t); return __builtin_bit_cast(unsigned, b); }
; DI float bf2f(unsigned b) { return __uint_as_float(b << 16); }
; DI float sigmoid_f(float x) { return __builtin_amdgcn_rcpf(1.f + __builtin_amdgcn_exp2f(x * -1.44269504089f)); }
; template <int N> DI void wait_vm() { asm volatile("s_waitcnt vmcnt(%0)" ::"n"(N) : "memory"); }
; DI size_t y_off(int tok, int col) { return ((size_t)(((tok >> 6) * 32 + (col >> 5)) * 64 + (tok & 63))) * 32 + (col & 31); }
; template <int NT2>
; DI void glu_prologue(const Params& p, char* lds, int l, int tile0, int tile1) {
;     ...
; #pragma unroll
;         for (int mt = 0; mt < 4; ++mt) {
;             const int tok = mt * 16 + l15;
; #pragma unroll
;             for (int nt = 0; nt < 2; ++nt) {
;                 const int n0 = wid * 32 + nt * 16 + quad * 4;
;                 const f32x4 gb = *(const f32x4*)(p.glu_b + l * 256 + n0);
;                 const u32x2 yv = *(const u32x2*)(Ys + tok * 528 + n0 * 2);
;                 const u32x2 sv = *(const u32x2*)(sg + (size_t)tok * 256 + n0);
;                 float o[4];
;                 o[0] = sigmoid_f(acc[tt][mt][nt][0] + gb[0]) * bf2f(yv[0] & 0xffffu) * bf2f(sv[0] & 0xffffu);
;                 o[1] = sigmoid_f(acc[tt][mt][nt][1] + gb[1]) * bf2f(yv[0] >> 16) * bf2f(sv[0] >> 16);
;                 o[2] = sigmoid_f(acc[tt][mt][nt][2] + gb[2]) * bf2f(yv[1] & 0xffffu) * bf2f(sv[1] & 0xffffu);
;                 o[3] = sigmoid_f(acc[tt][mt][nt][3] + gb[3]) * bf2f(yv[1] >> 16) * bf2f(sv[1] >> 16);
;                 *(u32x2*)(yo + y_off(tile * 64 + tok, 512 + n0)) = (u32x2){pk2(o[0], o[1]), pk2(o[2], o[3])};
;             }
;         }
;     }
;     wait_vm<0>();
	v_lshlrev_b32_e32 v14, 16, v22
	v_and_b32_e32 v15, 0xffff0000, v22
	v_lshlrev_b32_e32 v20, 16, v23
	v_and_b32_e32 v21, 0xffff0000, v23
	v_pk_mul_f32 v[16:17], v[16:17], v[26:27]
	v_pk_mul_f32 v[18:19], v[18:19], v[30:31]
	v_pk_mul_f32 v[14:15], v[16:17], v[14:15]
	v_pk_mul_f32 v[16:17], v[18:19], v[20:21]
	v_cvt_pk_bf16_f32 v14, v14, v15
	v_cvt_pk_bf16_f32 v15, v16, v17
	global_store_dwordx2 v[24:25], v[14:15], off
	global_load_dwordx4 v[14:17], v[72:73], off offset:64
	v_lshl_add_u64 v[18:19], v[28:29], 0, v[74:75]
	global_load_dwordx2 v[18:19], v[18:19], off offset:32
	v_lshlrev_b32_e32 v22, 16, v48
	v_and_b32_e32 v23, 0xffff0000, v48
	v_lshlrev_b32_e32 v26, 16, v49
	v_and_b32_e32 v27, 0xffff0000, v49
	v_lshl_add_u64 v[20:21], s[6:7], 0, v[50:51]
	s_waitcnt vmcnt(1)
	v_add_f32_e32 v14, v2, v14
	v_add_f32_e32 v15, v3, v15
	v_add_f32_e32 v4, v4, v16
	v_add_f32_e32 v5, v5, v17
	v_mul_f32_e32 v14, 0xbfb8aa3b, v14
	v_mul_f32_e32 v15, 0xbfb8aa3b, v15
	v_mul_f32_e32 v4, 0xbfb8aa3b, v4
	v_mul_f32_e32 v5, 0xbfb8aa3b, v5
	v_exp_f32_e32 v14, v14
	v_exp_f32_e32 v15, v15
	v_exp_f32_e32 v4, v4
	v_exp_f32_e32 v5, v5
	v_add_f32_e32 v14, 1.0, v14
	v_add_f32_e32 v15, 1.0, v15
	v_add_f32_e32 v16, 1.0, v4
	v_add_f32_e32 v17, 1.0, v5
	v_rcp_f32_e32 v4, v14
	v_rcp_f32_e32 v5, v15
	v_rcp_f32_e32 v14, v16
	v_rcp_f32_e32 v15, v17
	s_waitcnt vmcnt(0)
	v_lshlrev_b32_e32 v2, 16, v18
	v_and_b32_e32 v3, 0xffff0000, v18
	v_lshlrev_b32_e32 v16, 16, v19
	v_and_b32_e32 v17, 0xffff0000, v19
	v_pk_mul_f32 v[4:5], v[4:5], v[22:23]
	v_pk_mul_f32 v[14:15], v[14:15], v[26:27]
	v_pk_mul_f32 v[2:3], v[4:5], v[2:3]
	v_pk_mul_f32 v[4:5], v[14:15], v[16:17]
	v_cvt_pk_bf16_f32 v2, v2, v3
	v_cvt_pk_bf16_f32 v3, v4, v5
	global_store_dwordx2 v[24:25], v[2:3], off offset:32
	global_load_dwordx4 v[2:5], v[76:77], off
	v_lshl_add_u64 v[14:15], v[20:21], 0, v[80:81]
	global_load_dwordx2 v[14:15], v[14:15], off
	v_or_b32_e32 v16, v0, v59
	v_ashrrev_i32_e32 v17, 31, v16
	v_lshlrev_b32_e32 v18, 16, v44
	v_and_b32_e32 v19, 0xffff0000, v44
	v_lshlrev_b32_e32 v22, 16, v45
	v_and_b32_e32 v23, 0xffff0000, v45
	v_lshlrev_b64 v[16:17], 6, v[16:17]
	v_lshl_add_u64 v[16:17], s[54:55], 0, v[16:17]
	v_lshl_add_u64 v[16:17], v[16:17], 0, v[78:79]
	s_waitcnt vmcnt(1)
	v_add_f32_e32 v0, v10, v2
	v_add_f32_e32 v10, v11, v3
	v_add_f32_e32 v4, v12, v4
	v_add_f32_e32 v5, v13, v5
	v_mul_f32_e32 v0, 0xbfb8aa3b, v0
	v_mul_f32_e32 v10, 0xbfb8aa3b, v10
	v_mul_f32_e32 v4, 0xbfb8aa3b, v4
	v_mul_f32_e32 v5, 0xbfb8aa3b, v5
	v_exp_f32_e32 v0, v0
	v_exp_f32_e32 v10, v10
	v_exp_f32_e32 v4, v4
	v_exp_f32_e32 v5, v5
	v_add_f32_e32 v0, 1.0, v0
	v_add_f32_e32 v10, 1.0, v10
	v_add_f32_e32 v11, 1.0, v4
	v_add_f32_e32 v12, 1.0, v5
	v_rcp_f32_e32 v4, v0
	v_rcp_f32_e32 v5, v10
	v_rcp_f32_e32 v10, v11
	v_rcp_f32_e32 v11, v12
	s_waitcnt vmcnt(0)
	v_lshlrev_b32_e32 v2, 16, v14
	v_and_b32_e32 v3, 0xffff0000, v14
	v_lshlrev_b32_e32 v12, 16, v15
	v_and_b32_e32 v13, 0xffff0000, v15
	v_pk_mul_f32 v[4:5], v[4:5], v[18:19]
	v_pk_mul_f32 v[10:11], v[10:11], v[22:23]
	v_pk_mul_f32 v[2:3], v[4:5], v[2:3]
	v_pk_mul_f32 v[4:5], v[10:11], v[12:13]
	v_cvt_pk_bf16_f32 v2, v2, v3
	v_cvt_pk_bf16_f32 v3, v4, v5
	global_store_dwordx2 v[16:17], v[2:3], off
	global_load_dwordx4 v[2:5], v[72:73], off offset:64
	v_lshl_add_u64 v[10:11], v[20:21], 0, v[74:75]
	global_load_dwordx2 v[10:11], v[10:11], off offset:32
	v_lshlrev_b32_e32 v12, 16, v40
	v_and_b32_e32 v13, 0xffff0000, v40
	v_lshlrev_b32_e32 v14, 16, v41
	v_and_b32_e32 v15, 0xffff0000, v41
	s_waitcnt vmcnt(1)
	v_add_f32_e32 v0, v6, v2
	v_add_f32_e32 v6, v7, v3
	v_add_f32_e32 v4, v8, v4
	v_add_f32_e32 v5, v9, v5
	v_mul_f32_e32 v0, 0xbfb8aa3b, v0
	v_mul_f32_e32 v6, 0xbfb8aa3b, v6
	v_mul_f32_e32 v4, 0xbfb8aa3b, v4
	v_mul_f32_e32 v5, 0xbfb8aa3b, v5
	v_exp_f32_e32 v0, v0
	v_exp_f32_e32 v6, v6
	v_exp_f32_e32 v4, v4
	v_exp_f32_e32 v5, v5
	v_add_f32_e32 v0, 1.0, v0
	v_add_f32_e32 v6, 1.0, v6
	v_add_f32_e32 v7, 1.0, v4
	v_add_f32_e32 v8, 1.0, v5
	v_rcp_f32_e32 v4, v0
	v_rcp_f32_e32 v5, v6
	v_rcp_f32_e32 v6, v7
	v_rcp_f32_e32 v7, v8
	s_waitcnt vmcnt(0)
	v_lshlrev_b32_e32 v2, 16, v10
	v_and_b32_e32 v3, 0xffff0000, v10
	v_lshlrev_b32_e32 v8, 16, v11
	v_and_b32_e32 v9, 0xffff0000, v11
	v_pk_mul_f32 v[4:5], v[4:5], v[12:13]
	v_pk_mul_f32 v[6:7], v[6:7], v[14:15]
	v_pk_mul_f32 v[2:3], v[4:5], v[2:3]
	v_pk_mul_f32 v[4:5], v[6:7], v[8:9]
	v_cvt_pk_bf16_f32 v2, v2, v3
	v_cvt_pk_bf16_f32 v3, v4, v5
	global_store_dwordx2 v[16:17], v[2:3], off offset:32
	s_waitcnt vmcnt(0)
